# fence elision: no L2 write-back by the XCD leader at the barrier after the norm (the norm publishes H with write-through stores that every wave drains before arriving)
# speedup vs baseline: 1.0049x; 1.0049x over previous
; __device__ __forceinline__ unsigned xb_ld(unsigned* p)              { return __hip_atomic_load(p, __ATOMIC_RELAXED, __HIP_MEMORY_SCOPE_AGENT); }
; __device__ __forceinline__ unsigned xb_add(unsigned* p, unsigned v) { return __hip_atomic_fetch_add(p, v, __ATOMIC_RELAXED, __HIP_MEMORY_SCOPE_AGENT); }
; #define XB_SPIN(cond, bar) do { unsigned _sp = 0; while (cond) { __builtin_amdgcn_s_sleep(1); \
;     if ((++_sp & 255u) == 0u) { if (xb_ld(&(bar)[XB_TMO])) break; if (_sp > XB_SPIN_CAP) { atomicAdd(&(bar)[XB_TMO], 1u); break; } } } } while (0)
; __device__ __forceinline__ void xcd_barrier(const XcdBarrier& b) {
;     ...
;     if (threadIdx.x == 0) {
;         unsigned* bar = b.bar;
;         __builtin_amdgcn_s_waitcnt(0);
;         unsigned nloc = b.st[0], nx = b.st[1];
;         if (nloc == 0u) { xcd_barrier_complete(bar, b.x, nloc, nx); b.st[0] = nloc; b.st[1] = nx; }
;         const unsigned old = xb_add(&bar[XB_XSUB(b.x)], 1u);
;         const unsigned gen = old / nloc;
;         if (old + 1u == (gen + 1u) * nloc) {
;             __builtin_amdgcn_fence(__ATOMIC_RELEASE, "agent");
;             asm volatile("s_waitcnt vmcnt(0)" ::: "memory");
;             const unsigned og = xb_add(&bar[XB_TOP], 1u);
;             const unsigned tg = og / nx;
;             if (og + 1u == (tg + 1u) * nx) xb_add(&bar[XB_TOPGEN], 1u);
;             else XB_SPIN(xb_ld(&bar[XB_TOPGEN]) == tg, bar);
;             __builtin_amdgcn_fence(__ATOMIC_ACQUIRE, "agent");
;             xb_add(&bar[XB_XGEN(b.x)], 1u);
;             asm volatile("s_waitcnt vmcnt(0)" ::: "memory");
.LBB0_207:
	s_getreg_b32 s2, hwreg(HW_REG_XCC_ID, 0, 4)
	s_waitcnt vmcnt(0)
	s_barrier
	s_mov_b64 s[0:1], exec
	v_readlane_b32 s4, v253, 2
	v_readlane_b32 s5, v253, 3
	s_and_b64 s[4:5], s[0:1], s[4:5]
	s_mov_b64 exec, s[4:5]
	s_cbranch_execz .LBB0_259
	v_mov_b32_e32 v0, 0x20020
	s_waitcnt vmcnt(0) lgkmcnt(0)
	ds_read2_b32 v[2:3], v0 offset1:1
	s_and_b32 s3, s2, 15
	s_lshl_b32 s3, s3, 8
	s_add_u32 s6, s78, 0x1701400
	s_addc_u32 s7, s79, 0
	s_add_u32 s6, s6, s3
	s_addc_u32 s7, s7, 0
	s_add_u32 s8, s6, 0x1000
	s_addc_u32 s9, s7, 0
	s_add_u32 s10, s78, 0x1703400
	s_addc_u32 s11, s79, 0
	s_waitcnt lgkmcnt(0)
	v_readfirstlane_b32 s30, v2
	v_readfirstlane_b32 s31, v3
	s_nop 3
	s_cmp_eq_u32 s30, 0
	s_cbranch_scc1 .Lxb_slow_n
	s_lshl_b32 s29, s66, 2
	s_add_i32 s29, s29, 1
	global_atomic_add v2, v173, v212, s[6:7] sc0
	buffer_inv sc1
	s_add_i32 s32, s29, 1
	s_mul_i32 s5, s32, s30
	s_mul_i32 s32, s32, s31
	s_waitcnt vmcnt(1)
	v_readfirstlane_b32 s3, v2
	s_nop 3
	s_add_i32 s3, s3, 1
	s_cmp_lg_u32 s3, s5
	s_cbranch_scc1 .Lxb_local_n
	global_atomic_add v173, v212, s[10:11]
	s_mov_b32 s3, 0
